# norm phases: residual-stream row loads marked nontemporal (read once per phase)
# baseline (speedup 1.0000x reference)
.LBB0_632:
	v_lshl_add_u64 v[4:5], v[80:81], 0, v[78:79]
	global_load_dwordx4 v[64:67], v[4:5], off nt
	global_load_dwordx4 v[60:63], v[4:5], off offset:1024 nt
	global_load_dwordx4 v[56:59], v[4:5], off offset:2048 nt
	global_load_dwordx4 v[52:55], v[4:5], off offset:3072 nt
	v_add_u32_e32 v110, s68, v0
	s_movk_i32 s0, 0x4080
	v_cmp_gt_i32_e64 s[40:41], s0, v110
	v_mov_b32_e32 v16, 0
	v_mov_b32_e32 v36, 0
	v_mov_b32_e32 v37, 0
	v_mov_b32_e32 v38, 0
	v_mov_b32_e32 v39, 0
	v_mov_b32_e32 v40, 0
	v_mov_b32_e32 v41, 0
	v_mov_b32_e32 v42, 0
	v_mov_b32_e32 v43, 0
	v_mov_b32_e32 v44, 0
	v_mov_b32_e32 v45, 0
	v_mov_b32_e32 v46, 0
	v_mov_b32_e32 v47, 0
	v_mov_b32_e32 v48, 0
	v_mov_b32_e32 v49, 0
	v_mov_b32_e32 v50, 0
	v_mov_b32_e32 v51, 0
	s_and_saveexec_b64 s[0:1], s[40:41]
	s_cbranch_execz .LBB0_634
	v_lshl_add_u64 v[4:5], v[82:83], 0, v[78:79]
	global_load_dwordx4 v[48:51], v[4:5], off nt
	global_load_dwordx4 v[44:47], v[4:5], off offset:1024 nt
	global_load_dwordx4 v[40:43], v[4:5], off offset:2048 nt
	global_load_dwordx4 v[36:39], v[4:5], off offset:3072 nt
.LBB0_634:
	s_or_b64 exec, exec, s[0:1]
	v_add_u32_e32 v94, s55, v0
	s_movk_i32 s0, 0x4080
	v_cmp_gt_i32_e64 s[38:39], s0, v94
	v_ashrrev_i32_e32 v95, 31, v94
	v_mov_b32_e32 v17, 0
	v_mov_b32_e32 v18, 0
	v_mov_b32_e32 v19, 0
	v_mov_b32_e32 v24, 0
	v_mov_b32_e32 v25, 0
	v_mov_b32_e32 v26, 0
	v_mov_b32_e32 v27, 0
	v_mov_b32_e32 v28, 0
	v_mov_b32_e32 v29, 0
	v_mov_b32_e32 v30, 0
	v_mov_b32_e32 v31, 0
	v_mov_b32_e32 v32, 0
	v_mov_b32_e32 v33, 0
	v_mov_b32_e32 v34, 0
	v_mov_b32_e32 v35, 0
	s_and_saveexec_b64 s[0:1], s[38:39]
	s_cbranch_execz .LBB0_636
	v_lshlrev_b64 v[4:5], 12, v[94:95]
	v_lshl_add_u64 v[4:5], v[70:71], 0, v[4:5]
	global_load_dwordx4 v[32:35], v[4:5], off nt
	global_load_dwordx4 v[28:31], v[4:5], off offset:1024 nt
	global_load_dwordx4 v[24:27], v[4:5], off offset:2048 nt
	global_load_dwordx4 v[16:19], v[4:5], off offset:3072 nt
.LBB0_636:
	s_or_b64 exec, exec, s[0:1]
	v_readlane_b32 s0, v254, 55
	v_mov_b32_e32 v4, 0
	v_mov_b32_e32 v5, 0
	v_add_u32_e32 v92, s0, v0
	s_movk_i32 s0, 0x4080
	v_cmp_gt_i32_e32 vcc, s0, v92
	v_ashrrev_i32_e32 v93, 31, v92
	v_mov_b32_e32 v6, 0
	v_mov_b32_e32 v7, 0
	v_mov_b32_e32 v8, 0
	v_mov_b32_e32 v9, 0
	v_mov_b32_e32 v10, 0
	v_mov_b32_e32 v11, 0
	v_mov_b32_e32 v12, 0
	v_mov_b32_e32 v13, 0
	v_mov_b32_e32 v14, 0
	v_mov_b32_e32 v15, 0
	v_mov_b32_e32 v20, 0
	v_mov_b32_e32 v21, 0
	v_mov_b32_e32 v22, 0
	v_mov_b32_e32 v23, 0
	s_and_saveexec_b64 s[0:1], vcc
	s_cbranch_execz .LBB0_638
	v_lshlrev_b64 v[4:5], 12, v[92:93]
	v_lshl_add_u64 v[4:5], v[70:71], 0, v[4:5]
	global_load_dwordx4 v[20:23], v[4:5], off nt
	global_load_dwordx4 v[12:15], v[4:5], off offset:1024 nt
	global_load_dwordx4 v[8:11], v[4:5], off offset:2048 nt
	s_nop 0
	global_load_dwordx4 v[4:7], v[4:5], off offset:3072 nt

.LBB0_716:
	v_lshlrev_b64 v[4:5], 12, v[4:5]
	v_lshl_add_u64 v[4:5], v[6:7], 0, v[4:5]
	v_lshlrev_b32_e32 v82, 2, v68
	v_mov_b32_e32 v83, v2
	v_lshl_add_u64 v[4:5], v[4:5], 0, v[82:83]
	flat_load_dwordx4 v[64:67], v[4:5] nt
	flat_load_dwordx4 v[60:63], v[4:5] offset:1024 nt
	flat_load_dwordx4 v[56:59], v[4:5] offset:2048 nt
	flat_load_dwordx4 v[52:55], v[4:5] offset:3072 nt
	v_add_u32_e32 v94, s68, v72
	v_add_u32_e32 v92, 0x4000, v94
	s_movk_i32 s10, 0x4080
	v_cndmask_b32_e64 v4, 0, 1, s[6:7]
	v_cmp_gt_i32_e64 s[42:43], s10, v92
	v_mov_b32_e32 v51, 0
	v_cmp_ne_u32_e64 s[44:45], 1, v4
	v_mov_b32_e32 v50, 0
	v_mov_b32_e32 v49, 0
	v_mov_b32_e32 v48, 0
	v_mov_b32_e32 v47, 0
	v_mov_b32_e32 v46, 0
	v_mov_b32_e32 v45, 0
	v_mov_b32_e32 v44, 0
	v_mov_b32_e32 v43, 0
	v_mov_b32_e32 v42, 0
	v_mov_b32_e32 v41, 0
	v_mov_b32_e32 v40, 0
	v_mov_b32_e32 v35, 0
	v_mov_b32_e32 v34, 0
	v_mov_b32_e32 v33, 0
	v_mov_b32_e32 v32, 0
	s_and_saveexec_b64 s[10:11], s[42:43]
	s_cbranch_execz .LBB0_726
	s_and_b64 vcc, exec, s[44:45]
	s_mov_b64 s[12:13], -1
	s_cbranch_vccnz .LBB0_719
	v_ashrrev_i32_e32 v93, 31, v92
	s_mov_b64 s[12:13], 0
	v_mov_b64_e32 v[4:5], v[92:93]

.LBB0_725:
	v_lshlrev_b64 v[4:5], 12, v[4:5]
	v_lshl_add_u64 v[4:5], v[6:7], 0, v[4:5]
	v_mov_b32_e32 v83, v2
	v_lshl_add_u64 v[4:5], v[4:5], 0, v[82:83]
	flat_load_dwordx4 v[48:51], v[4:5] nt
	flat_load_dwordx4 v[44:47], v[4:5] offset:1024 nt
	flat_load_dwordx4 v[40:43], v[4:5] offset:2048 nt
	flat_load_dwordx4 v[32:35], v[4:5] offset:3072 nt

.LBB0_735:
	v_lshlrev_b64 v[4:5], 12, v[4:5]
	v_lshl_add_u64 v[4:5], v[6:7], 0, v[4:5]
	v_mov_b32_e32 v83, v2
	v_lshl_add_u64 v[4:5], v[4:5], 0, v[82:83]
	flat_load_dwordx4 v[36:39], v[4:5] nt
	flat_load_dwordx4 v[28:31], v[4:5] offset:1024 nt
	flat_load_dwordx4 v[24:27], v[4:5] offset:2048 nt
	flat_load_dwordx4 v[16:19], v[4:5] offset:3072 nt

.LBB0_745:
	v_lshlrev_b64 v[4:5], 12, v[4:5]
	v_lshl_add_u64 v[4:5], v[6:7], 0, v[4:5]
	v_mov_b32_e32 v83, v2
	v_lshl_add_u64 v[4:5], v[4:5], 0, v[82:83]
	flat_load_dwordx4 v[20:23], v[4:5] nt
	flat_load_dwordx4 v[12:15], v[4:5] offset:1024 nt
	flat_load_dwordx4 v[8:11], v[4:5] offset:2048 nt
	s_nop 0
	flat_load_dwordx4 v[4:7], v[4:5] offset:3072 nt
